# removed hipcc's conservative s_waitcnt vmcnt(0) in the unit-loop headers of 4 GEMM phases (P1, P3 x2, P8): the template's counted waits already cover the in-flight tile loads
# speedup vs baseline: 1.0032x; 1.0032x over previous
.LBB0_166:
	s_ashr_i32 s25, s24, 31
	s_lshl_b64 s[26:27], s[24:25], 20
	s_add_u32 s26, s52, s26
	s_addc_u32 s27, s53, s27
	s_and_b64 s[28:29], s[6:7], exec
	s_cselect_b32 s25, s27, s31
	s_cselect_b32 s62, s26, s30
	s_ashr_i32 s23, s22, 31
	s_lshl_b64 s[28:29], s[22:23], 20
	s_add_u32 s28, s10, s28
	s_addc_u32 s29, s11, s29
	s_and_b64 s[36:37], s[6:7], exec
	s_cselect_b32 s23, s29, s35
	s_cselect_b32 s63, s28, s34
	s_add_u32 s30, s30, 0x80080
	s_addc_u32 s31, s31, 0
	s_add_u32 s70, s34, 0x100
	v_mov_b32_e32 v0, 0
	s_addc_u32 s71, s35, 0
	s_mov_b32 s72, -2
	v_mov_b32_e32 v1, v0
	v_mov_b32_e32 v2, v0
	v_mov_b32_e32 v3, v0
	v_mov_b32_e32 v8, v0
	v_mov_b32_e32 v9, v0
	v_mov_b32_e32 v10, v0
	v_mov_b32_e32 v11, v0
	v_mov_b32_e32 v16, v0
	v_mov_b32_e32 v17, v0
	v_mov_b32_e32 v18, v0
	v_mov_b32_e32 v19, v0
	v_mov_b32_e32 v24, v0
	v_mov_b32_e32 v25, v0
	v_mov_b32_e32 v26, v0
	v_mov_b32_e32 v27, v0
	v_mov_b32_e32 v32, v0
	v_mov_b32_e32 v33, v0
	v_mov_b32_e32 v34, v0
	v_mov_b32_e32 v35, v0
	v_mov_b32_e32 v40, v0
	v_mov_b32_e32 v41, v0
	v_mov_b32_e32 v42, v0
	v_mov_b32_e32 v43, v0
	v_mov_b32_e32 v48, v0
	v_mov_b32_e32 v49, v0
	v_mov_b32_e32 v50, v0
	v_mov_b32_e32 v51, v0
	v_mov_b32_e32 v56, v0
	v_mov_b32_e32 v57, v0
	v_mov_b32_e32 v58, v0
	v_mov_b32_e32 v59, v0
	v_mov_b32_e32 v4, v0
	v_mov_b32_e32 v5, v0
	v_mov_b32_e32 v6, v0
	v_mov_b32_e32 v7, v0
	v_mov_b32_e32 v12, v0
	v_mov_b32_e32 v13, v0
	v_mov_b32_e32 v14, v0
	v_mov_b32_e32 v15, v0
	v_mov_b32_e32 v20, v0
	v_mov_b32_e32 v21, v0
	v_mov_b32_e32 v22, v0
	v_mov_b32_e32 v23, v0
	v_mov_b32_e32 v28, v0
	v_mov_b32_e32 v29, v0
	v_mov_b32_e32 v30, v0
	v_mov_b32_e32 v31, v0
	v_mov_b32_e32 v36, v0
	v_mov_b32_e32 v37, v0
	v_mov_b32_e32 v38, v0
	v_mov_b32_e32 v39, v0
	v_mov_b32_e32 v44, v0
	v_mov_b32_e32 v45, v0
	v_mov_b32_e32 v46, v0
	v_mov_b32_e32 v47, v0
	v_mov_b32_e32 v52, v0
	v_mov_b32_e32 v53, v0
	v_mov_b32_e32 v54, v0
	v_mov_b32_e32 v55, v0
	v_mov_b32_e32 v60, v0
	v_mov_b32_e32 v61, v0
	v_mov_b32_e32 v62, v0
	v_mov_b32_e32 v63, v0
	v_mov_b32_e32 v64, v0
	v_mov_b32_e32 v65, v0
	v_mov_b32_e32 v66, v0
	v_mov_b32_e32 v67, v0
	v_mov_b32_e32 v72, v0
	v_mov_b32_e32 v73, v0
	v_mov_b32_e32 v74, v0
	v_mov_b32_e32 v75, v0
	v_mov_b32_e32 v80, v0
	v_mov_b32_e32 v81, v0
	v_mov_b32_e32 v82, v0
	v_mov_b32_e32 v83, v0
	v_mov_b32_e32 v88, v0
	v_mov_b32_e32 v89, v0
	v_mov_b32_e32 v90, v0
	v_mov_b32_e32 v91, v0
	v_mov_b32_e32 v96, v0
	v_mov_b32_e32 v97, v0
	v_mov_b32_e32 v98, v0
	v_mov_b32_e32 v99, v0
	v_mov_b32_e32 v104, v0
	v_mov_b32_e32 v105, v0
	v_mov_b32_e32 v106, v0
	v_mov_b32_e32 v107, v0
	v_mov_b32_e32 v108, v0
	v_mov_b32_e32 v109, v0
	v_mov_b32_e32 v110, v0
	v_mov_b32_e32 v111, v0
	v_mov_b32_e32 v112, v0
	v_mov_b32_e32 v113, v0
	v_mov_b32_e32 v114, v0
	v_mov_b32_e32 v115, v0
	v_mov_b32_e32 v68, v0
	v_mov_b32_e32 v69, v0
	v_mov_b32_e32 v70, v0
	v_mov_b32_e32 v71, v0
	v_mov_b32_e32 v76, v0
	v_mov_b32_e32 v77, v0
	v_mov_b32_e32 v78, v0
	v_mov_b32_e32 v79, v0
	v_mov_b32_e32 v84, v0
	v_mov_b32_e32 v85, v0
	v_mov_b32_e32 v86, v0
	v_mov_b32_e32 v87, v0
	v_mov_b32_e32 v92, v0
	v_mov_b32_e32 v93, v0
	v_mov_b32_e32 v94, v0
	v_mov_b32_e32 v95, v0
	v_mov_b32_e32 v100, v0
	v_mov_b32_e32 v101, v0
	v_mov_b32_e32 v102, v0
	v_mov_b32_e32 v103, v0
	v_mov_b32_e32 v116, v0
	v_mov_b32_e32 v117, v0
	v_mov_b32_e32 v118, v0
	v_mov_b32_e32 v119, v0
	v_mov_b32_e32 v120, v0
	v_mov_b32_e32 v121, v0
	v_mov_b32_e32 v122, v0
	v_mov_b32_e32 v123, v0
	v_mov_b32_e32 v124, v0
	v_mov_b32_e32 v125, v0
	v_mov_b32_e32 v126, v0
	v_mov_b32_e32 v127, v0

.LBB0_453:
	s_ashr_i32 s27, s26, 31
	s_lshl_b64 s[28:29], s[26:27], 20
	s_add_u32 s28, s52, s28
	s_addc_u32 s29, s53, s29
	s_and_b64 s[30:31], s[6:7], exec
	s_cselect_b32 s9, s29, s37
	s_cselect_b32 s10, s28, s36
	s_ashr_i32 s25, s24, 31
	s_lshl_b64 s[30:31], s[24:25], 20
	s_add_u32 s30, s44, s30
	s_addc_u32 s31, s45, s31
	s_and_b64 s[40:41], s[6:7], exec
	s_cselect_b32 s25, s31, s39
	s_cselect_b32 s27, s30, s38
	s_add_u32 s36, s36, 0x80080
	s_addc_u32 s37, s37, 0
	s_add_u32 s35, s38, 0x100
	v_mov_b32_e32 v0, 0
	s_addc_u32 s62, s39, 0
	s_mov_b32 s63, -2
	v_mov_b32_e32 v1, v0
	v_mov_b32_e32 v2, v0
	v_mov_b32_e32 v3, v0
	v_mov_b32_e32 v4, v0
	v_mov_b32_e32 v5, v0
	v_mov_b32_e32 v6, v0
	v_mov_b32_e32 v7, v0
	v_mov_b32_e32 v16, v0
	v_mov_b32_e32 v17, v0
	v_mov_b32_e32 v18, v0
	v_mov_b32_e32 v19, v0
	v_mov_b32_e32 v20, v0
	v_mov_b32_e32 v21, v0
	v_mov_b32_e32 v22, v0
	v_mov_b32_e32 v23, v0
	v_mov_b32_e32 v32, v0
	v_mov_b32_e32 v33, v0
	v_mov_b32_e32 v34, v0
	v_mov_b32_e32 v35, v0
	v_mov_b32_e32 v36, v0
	v_mov_b32_e32 v37, v0
	v_mov_b32_e32 v38, v0
	v_mov_b32_e32 v39, v0
	v_mov_b32_e32 v48, v0
	v_mov_b32_e32 v49, v0
	v_mov_b32_e32 v50, v0
	v_mov_b32_e32 v51, v0
	v_mov_b32_e32 v52, v0
	v_mov_b32_e32 v53, v0
	v_mov_b32_e32 v54, v0
	v_mov_b32_e32 v55, v0
	v_mov_b32_e32 v8, v0
	v_mov_b32_e32 v9, v0
	v_mov_b32_e32 v10, v0
	v_mov_b32_e32 v11, v0
	v_mov_b32_e32 v12, v0
	v_mov_b32_e32 v13, v0
	v_mov_b32_e32 v14, v0
	v_mov_b32_e32 v15, v0
	v_mov_b32_e32 v24, v0
	v_mov_b32_e32 v25, v0
	v_mov_b32_e32 v26, v0
	v_mov_b32_e32 v27, v0
	v_mov_b32_e32 v28, v0
	v_mov_b32_e32 v29, v0
	v_mov_b32_e32 v30, v0
	v_mov_b32_e32 v31, v0
	v_mov_b32_e32 v40, v0
	v_mov_b32_e32 v41, v0
	v_mov_b32_e32 v42, v0
	v_mov_b32_e32 v43, v0
	v_mov_b32_e32 v44, v0
	v_mov_b32_e32 v45, v0
	v_mov_b32_e32 v46, v0
	v_mov_b32_e32 v47, v0
	v_mov_b32_e32 v56, v0
	v_mov_b32_e32 v57, v0
	v_mov_b32_e32 v58, v0
	v_mov_b32_e32 v59, v0
	v_mov_b32_e32 v60, v0
	v_mov_b32_e32 v61, v0
	v_mov_b32_e32 v62, v0
	v_mov_b32_e32 v63, v0
	v_mov_b32_e32 v64, v0
	v_mov_b32_e32 v65, v0
	v_mov_b32_e32 v66, v0
	v_mov_b32_e32 v67, v0
	v_mov_b32_e32 v68, v0
	v_mov_b32_e32 v69, v0
	v_mov_b32_e32 v70, v0
	v_mov_b32_e32 v71, v0
	v_mov_b32_e32 v80, v0
	v_mov_b32_e32 v81, v0
	v_mov_b32_e32 v82, v0
	v_mov_b32_e32 v83, v0
	v_mov_b32_e32 v84, v0
	v_mov_b32_e32 v85, v0
	v_mov_b32_e32 v86, v0
	v_mov_b32_e32 v87, v0
	v_mov_b32_e32 v96, v0
	v_mov_b32_e32 v97, v0
	v_mov_b32_e32 v98, v0
	v_mov_b32_e32 v99, v0
	v_mov_b32_e32 v100, v0
	v_mov_b32_e32 v101, v0
	v_mov_b32_e32 v102, v0
	v_mov_b32_e32 v103, v0
	v_mov_b32_e32 v112, v0
	v_mov_b32_e32 v113, v0
	v_mov_b32_e32 v114, v0
	v_mov_b32_e32 v115, v0
	v_mov_b32_e32 v116, v0
	v_mov_b32_e32 v117, v0
	v_mov_b32_e32 v118, v0
	v_mov_b32_e32 v119, v0
	v_mov_b32_e32 v72, v0
	v_mov_b32_e32 v73, v0
	v_mov_b32_e32 v74, v0
	v_mov_b32_e32 v75, v0
	v_mov_b32_e32 v76, v0
	v_mov_b32_e32 v77, v0
	v_mov_b32_e32 v78, v0
	v_mov_b32_e32 v79, v0
	v_mov_b32_e32 v88, v0
	v_mov_b32_e32 v89, v0
	v_mov_b32_e32 v90, v0
	v_mov_b32_e32 v91, v0
	v_mov_b32_e32 v92, v0
	v_mov_b32_e32 v93, v0
	v_mov_b32_e32 v94, v0
	v_mov_b32_e32 v95, v0
	v_mov_b32_e32 v104, v0
	v_mov_b32_e32 v105, v0
	v_mov_b32_e32 v106, v0
	v_mov_b32_e32 v107, v0
	v_mov_b32_e32 v108, v0
	v_mov_b32_e32 v109, v0
	v_mov_b32_e32 v110, v0
	v_mov_b32_e32 v111, v0
	v_mov_b32_e32 v120, v0
	v_mov_b32_e32 v121, v0
	v_mov_b32_e32 v122, v0
	v_mov_b32_e32 v123, v0
	v_mov_b32_e32 v124, v0
	v_mov_b32_e32 v125, v0
	v_mov_b32_e32 v126, v0
	v_mov_b32_e32 v127, v0

.LBB0_541:
	s_ashr_i32 s27, s26, 31
	s_lshl_b64 s[28:29], s[26:27], 20
	s_add_u32 s28, s23, s28
	s_addc_u32 s29, s40, s29
	s_and_b64 s[30:31], s[6:7], exec
	s_cselect_b32 s27, s29, s9
	s_cselect_b32 s62, s28, s8
	s_ashr_i32 s25, s24, 31
	s_lshl_b64 s[30:31], s[24:25], 20
	s_add_u32 s30, s52, s30
	s_addc_u32 s31, s53, s31
	s_and_b64 s[38:39], s[6:7], exec
	s_cselect_b32 s25, s31, s37
	s_cselect_b32 s63, s30, s36
	s_add_u32 s8, s8, 0x80080
	s_addc_u32 s9, s9, 0
	s_add_u32 s79, s36, 0x100
	v_mov_b32_e32 v0, 0
	s_addc_u32 s80, s37, 0
	s_mov_b32 s81, -2
	v_mov_b32_e32 v1, v0
	v_mov_b32_e32 v2, v0
	v_mov_b32_e32 v3, v0
	v_mov_b32_e32 v4, v0
	v_mov_b32_e32 v5, v0
	v_mov_b32_e32 v6, v0
	v_mov_b32_e32 v7, v0
	v_mov_b32_e32 v12, v0
	v_mov_b32_e32 v13, v0
	v_mov_b32_e32 v14, v0
	v_mov_b32_e32 v15, v0
	v_mov_b32_e32 v20, v0
	v_mov_b32_e32 v21, v0
	v_mov_b32_e32 v22, v0
	v_mov_b32_e32 v23, v0
	v_mov_b32_e32 v28, v0
	v_mov_b32_e32 v29, v0
	v_mov_b32_e32 v30, v0
	v_mov_b32_e32 v31, v0
	v_mov_b32_e32 v36, v0
	v_mov_b32_e32 v37, v0
	v_mov_b32_e32 v38, v0
	v_mov_b32_e32 v39, v0
	v_mov_b32_e32 v44, v0
	v_mov_b32_e32 v45, v0
	v_mov_b32_e32 v46, v0
	v_mov_b32_e32 v47, v0
	v_mov_b32_e32 v52, v0
	v_mov_b32_e32 v53, v0
	v_mov_b32_e32 v54, v0
	v_mov_b32_e32 v55, v0
	v_mov_b32_e32 v8, v0
	v_mov_b32_e32 v9, v0
	v_mov_b32_e32 v10, v0
	v_mov_b32_e32 v11, v0
	v_mov_b32_e32 v16, v0
	v_mov_b32_e32 v17, v0
	v_mov_b32_e32 v18, v0
	v_mov_b32_e32 v19, v0
	v_mov_b32_e32 v24, v0
	v_mov_b32_e32 v25, v0
	v_mov_b32_e32 v26, v0
	v_mov_b32_e32 v27, v0
	v_mov_b32_e32 v32, v0
	v_mov_b32_e32 v33, v0
	v_mov_b32_e32 v34, v0
	v_mov_b32_e32 v35, v0
	v_mov_b32_e32 v40, v0
	v_mov_b32_e32 v41, v0
	v_mov_b32_e32 v42, v0
	v_mov_b32_e32 v43, v0
	v_mov_b32_e32 v48, v0
	v_mov_b32_e32 v49, v0
	v_mov_b32_e32 v50, v0
	v_mov_b32_e32 v51, v0
	v_mov_b32_e32 v56, v0
	v_mov_b32_e32 v57, v0
	v_mov_b32_e32 v58, v0
	v_mov_b32_e32 v59, v0
	v_mov_b32_e32 v60, v0
	v_mov_b32_e32 v61, v0
	v_mov_b32_e32 v62, v0
	v_mov_b32_e32 v63, v0
	v_mov_b32_e32 v64, v0
	v_mov_b32_e32 v65, v0
	v_mov_b32_e32 v66, v0
	v_mov_b32_e32 v67, v0
	v_mov_b32_e32 v68, v0
	v_mov_b32_e32 v69, v0
	v_mov_b32_e32 v70, v0
	v_mov_b32_e32 v71, v0
	v_mov_b32_e32 v76, v0
	v_mov_b32_e32 v77, v0
	v_mov_b32_e32 v78, v0
	v_mov_b32_e32 v79, v0
	v_mov_b32_e32 v84, v0
	v_mov_b32_e32 v85, v0
	v_mov_b32_e32 v86, v0
	v_mov_b32_e32 v87, v0
	v_mov_b32_e32 v92, v0
	v_mov_b32_e32 v93, v0
	v_mov_b32_e32 v94, v0
	v_mov_b32_e32 v95, v0
	v_mov_b32_e32 v100, v0
	v_mov_b32_e32 v101, v0
	v_mov_b32_e32 v102, v0
	v_mov_b32_e32 v103, v0
	v_mov_b32_e32 v108, v0
	v_mov_b32_e32 v109, v0
	v_mov_b32_e32 v110, v0
	v_mov_b32_e32 v111, v0
	v_mov_b32_e32 v116, v0
	v_mov_b32_e32 v117, v0
	v_mov_b32_e32 v118, v0
	v_mov_b32_e32 v119, v0
	v_mov_b32_e32 v72, v0
	v_mov_b32_e32 v73, v0
	v_mov_b32_e32 v74, v0
	v_mov_b32_e32 v75, v0
	v_mov_b32_e32 v80, v0
	v_mov_b32_e32 v81, v0
	v_mov_b32_e32 v82, v0
	v_mov_b32_e32 v83, v0
	v_mov_b32_e32 v88, v0
	v_mov_b32_e32 v89, v0
	v_mov_b32_e32 v90, v0
	v_mov_b32_e32 v91, v0
	v_mov_b32_e32 v96, v0
	v_mov_b32_e32 v97, v0
	v_mov_b32_e32 v98, v0
	v_mov_b32_e32 v99, v0
	v_mov_b32_e32 v104, v0
	v_mov_b32_e32 v105, v0
	v_mov_b32_e32 v106, v0
	v_mov_b32_e32 v107, v0
	v_mov_b32_e32 v112, v0
	v_mov_b32_e32 v113, v0
	v_mov_b32_e32 v114, v0
	v_mov_b32_e32 v115, v0
	v_mov_b32_e32 v120, v0
	v_mov_b32_e32 v121, v0
	v_mov_b32_e32 v122, v0
	v_mov_b32_e32 v123, v0
	v_mov_b32_e32 v124, v0
	v_mov_b32_e32 v125, v0
	v_mov_b32_e32 v126, v0
	v_mov_b32_e32 v127, v0

.LBB0_1355:
	s_ashr_i32 s25, s24, 31
	s_lshl_b64 s[26:27], s[24:25], 20
	s_add_u32 s26, s52, s26
	s_addc_u32 s27, s53, s27
	s_and_b64 s[28:29], s[4:5], exec
	s_cselect_b32 s9, s27, s35
	s_cselect_b32 s25, s26, s34
	s_ashr_i32 s23, s22, 31
	s_lshl_b64 s[28:29], s[22:23], 20
	s_add_u32 s28, s40, s28
	s_addc_u32 s29, s41, s29
	s_and_b64 s[38:39], s[4:5], exec
	s_cselect_b32 s23, s29, s37
	s_cselect_b32 s31, s28, s36
	s_add_u32 s34, s34, 0x80080
	s_addc_u32 s35, s35, 0
	s_add_u32 s62, s36, 0x100
	v_mov_b32_e32 v0, 0
	s_addc_u32 s63, s37, 0
	s_mov_b32 s64, -2
	v_mov_b32_e32 v1, v0
	v_mov_b32_e32 v2, v0
	v_mov_b32_e32 v3, v0
	v_mov_b32_e32 v4, v0
	v_mov_b32_e32 v5, v0
	v_mov_b32_e32 v6, v0
	v_mov_b32_e32 v7, v0
	v_mov_b32_e32 v16, v0
	v_mov_b32_e32 v17, v0
	v_mov_b32_e32 v18, v0
	v_mov_b32_e32 v19, v0
	v_mov_b32_e32 v20, v0
	v_mov_b32_e32 v21, v0
	v_mov_b32_e32 v22, v0
	v_mov_b32_e32 v23, v0
	v_mov_b32_e32 v32, v0
	v_mov_b32_e32 v33, v0
	v_mov_b32_e32 v34, v0
	v_mov_b32_e32 v35, v0
	v_mov_b32_e32 v36, v0
	v_mov_b32_e32 v37, v0
	v_mov_b32_e32 v38, v0
	v_mov_b32_e32 v39, v0
	v_mov_b32_e32 v48, v0
	v_mov_b32_e32 v49, v0
	v_mov_b32_e32 v50, v0
	v_mov_b32_e32 v51, v0
	v_mov_b32_e32 v52, v0
	v_mov_b32_e32 v53, v0
	v_mov_b32_e32 v54, v0
	v_mov_b32_e32 v55, v0
	v_mov_b32_e32 v8, v0
	v_mov_b32_e32 v9, v0
	v_mov_b32_e32 v10, v0
	v_mov_b32_e32 v11, v0
	v_mov_b32_e32 v12, v0
	v_mov_b32_e32 v13, v0
	v_mov_b32_e32 v14, v0
	v_mov_b32_e32 v15, v0
	v_mov_b32_e32 v24, v0
	v_mov_b32_e32 v25, v0
	v_mov_b32_e32 v26, v0
	v_mov_b32_e32 v27, v0
	v_mov_b32_e32 v28, v0
	v_mov_b32_e32 v29, v0
	v_mov_b32_e32 v30, v0
	v_mov_b32_e32 v31, v0
	v_mov_b32_e32 v40, v0
	v_mov_b32_e32 v41, v0
	v_mov_b32_e32 v42, v0
	v_mov_b32_e32 v43, v0
	v_mov_b32_e32 v44, v0
	v_mov_b32_e32 v45, v0
	v_mov_b32_e32 v46, v0
	v_mov_b32_e32 v47, v0
	v_mov_b32_e32 v56, v0
	v_mov_b32_e32 v57, v0
	v_mov_b32_e32 v58, v0
	v_mov_b32_e32 v59, v0
	v_mov_b32_e32 v60, v0
	v_mov_b32_e32 v61, v0
	v_mov_b32_e32 v62, v0
	v_mov_b32_e32 v63, v0
	v_mov_b32_e32 v64, v0
	v_mov_b32_e32 v65, v0
	v_mov_b32_e32 v66, v0
	v_mov_b32_e32 v67, v0
	v_mov_b32_e32 v68, v0
	v_mov_b32_e32 v69, v0
	v_mov_b32_e32 v70, v0
	v_mov_b32_e32 v71, v0
	v_mov_b32_e32 v80, v0
	v_mov_b32_e32 v81, v0
	v_mov_b32_e32 v82, v0
	v_mov_b32_e32 v83, v0
	v_mov_b32_e32 v84, v0
	v_mov_b32_e32 v85, v0
	v_mov_b32_e32 v86, v0
	v_mov_b32_e32 v87, v0
	v_mov_b32_e32 v96, v0
	v_mov_b32_e32 v97, v0
	v_mov_b32_e32 v98, v0
	v_mov_b32_e32 v99, v0
	v_mov_b32_e32 v100, v0
	v_mov_b32_e32 v101, v0
	v_mov_b32_e32 v102, v0
	v_mov_b32_e32 v103, v0
	v_mov_b32_e32 v112, v0
	v_mov_b32_e32 v113, v0
	v_mov_b32_e32 v114, v0
	v_mov_b32_e32 v115, v0
	v_mov_b32_e32 v116, v0
	v_mov_b32_e32 v117, v0
	v_mov_b32_e32 v118, v0
	v_mov_b32_e32 v119, v0
	v_mov_b32_e32 v72, v0
	v_mov_b32_e32 v73, v0
	v_mov_b32_e32 v74, v0
	v_mov_b32_e32 v75, v0
	v_mov_b32_e32 v76, v0
	v_mov_b32_e32 v77, v0
	v_mov_b32_e32 v78, v0
	v_mov_b32_e32 v79, v0
	v_mov_b32_e32 v88, v0
	v_mov_b32_e32 v89, v0
	v_mov_b32_e32 v90, v0
	v_mov_b32_e32 v91, v0
	v_mov_b32_e32 v92, v0
	v_mov_b32_e32 v93, v0
	v_mov_b32_e32 v94, v0
	v_mov_b32_e32 v95, v0
	v_mov_b32_e32 v104, v0
	v_mov_b32_e32 v105, v0
	v_mov_b32_e32 v106, v0
	v_mov_b32_e32 v107, v0
	v_mov_b32_e32 v108, v0
	v_mov_b32_e32 v109, v0
	v_mov_b32_e32 v110, v0
	v_mov_b32_e32 v111, v0
	v_mov_b32_e32 v120, v0
	v_mov_b32_e32 v121, v0
	v_mov_b32_e32 v122, v0
	v_mov_b32_e32 v123, v0
	v_mov_b32_e32 v124, v0
	v_mov_b32_e32 v125, v0
	v_mov_b32_e32 v126, v0
	v_mov_b32_e32 v127, v0
